# layer-0 out-GEMM: the 32 residual stores issued inside the normalise section (4 per row group, counted waits 14+4g) instead of one burst before the poll; on top of the fourth combination
# speedup vs baseline: 1.0021x; 1.0021x over previous
;     __device__ __forceinline__ void operator()(f32x4 (&acc)[2][2][4][2], const Unit& u, int wr, int wc, int fr, int fq) const {
;     ...
;         asm volatile("s_waitcnt vmcnt(0)" ::: "memory");
;         unsigned* cnt = CNT + 16 * u.pm;
;         if (fr == 0 && fq == 0) __hip_atomic_fetch_add(cnt, 1u, __ATOMIC_RELAXED, __HIP_MEMORY_SCOPE_AGENT);
;         asm volatile("" ::: "memory");
;         float* ob = out + (size_t)row0 * 1024 + col0; asm volatile("" : "+v"(ob));
;         if constexpr (!FINAL) {
; #pragma unroll
;             for (int ai = 0; ai < 2; ++ai)
; #pragma unroll
;                 for (int m = 0; m < 4; ++m)
; #pragma unroll
;                     for (int bj = 0; bj < 2; ++bj) { float* op = ob + ((ai * HALF + m * 16) * 1024 + bj * HALF);
;                         *(f32x4*)op = acc[ai][bj][m][0]; *(f32x4*)(op + 4) = acc[ai][bj][m][1]; asm volatile("" ::: "memory"); }
;         }
;         if (fr == 0 && fq == 0) {
;             unsigned spins = 0;
;             while (__hip_atomic_load(cnt, __ATOMIC_RELAXED, __HIP_MEMORY_SCOPE_AGENT) < 32u) { __builtin_amdgcn_s_sleep(2); if (++spins > (1u << 20)) break; }
;         }
.LBB0_1408:
	s_or_b64 exec, exec, s[2:3]
	s_waitcnt lgkmcnt(0)
	s_and_saveexec_b64 s[2:3], s[6:7]
	s_cbranch_execz .LBB0_1422
	s_mov_b32 s9, 0x100000
	s_branch .LBB0_1412

;     __device__ __forceinline__ void operator()(f32x4 (&acc)[2][2][4][2], const Unit& u, int wr, int wc, int fr, int fq) const {
;     ...
; #pragma unroll
;         for (int ai = 0; ai < 2; ++ai)
; #pragma unroll
;             for (int m = 0; m < 4; ++m) {
;                 const int row = row0 + ai * HALF + m * 16;
;                 const float ss = __hip_atomic_load(SS + row, __ATOMIC_RELAXED, __HIP_MEMORY_SCOPE_AGENT);
;                 const float rstd = 1.0f / sqrtf(ss * (1.f / 1024.f) + 1e-6f);
;                 float qs = 0.f;
;                 if constexpr (!FINAL) {
;                     const float am = __uint_as_float(__hip_atomic_load(AM + row, __ATOMIC_RELAXED, __HIP_MEMORY_SCOPE_AGENT));
;                     qs = am > 0.f ? 127.f / am : 0.f;
;                     if (u.pn == 0 && wc == 0 && fq == 0) SH[row] = am * rstd * (1.f / 127.f);
;                 }
; #pragma unroll
;                 for (int bj = 0; bj < 2; ++bj) {
;                     const size_t off = (size_t)row * 1024 + col0 + bj * HALF;
;                     const f32x4 y0 = acc[ai][bj][m][0] * rstd * gv[bj][0], y1 = acc[ai][bj][m][1] * rstd * gv[bj][1];
;                     if constexpr (FINAL) { *(f32x4*)(out + off) = y0; *(f32x4*)(out + off + 4) = y1; }
;                     else {
;                         u32x2 q8; q8.x = q8x4(acc[ai][bj][m][0] * gv[bj][0], qs); q8.y = q8x4(acc[ai][bj][m][1] * gv[bj][1], qs);
;                         *(u32x2*)(H8 + off) = q8;
;                     }
;                 }
.LBB0_1422:
	s_or_b64 exec, exec, s[2:3]
	v_lshlrev_b64 v[148:149], 2, v[224:225]
	v_lshl_add_u64 v[146:147], s[22:23], 0, v[148:149]
	v_lshl_add_u64 v[148:149], s[24:25], 0, v[148:149]
	global_load_dword v158, v[146:147], off sc1
	global_load_dword v159, v[148:149], off sc1
	global_load_dword v160, v[146:147], off offset:64 sc1
	global_load_dword v161, v[148:149], off offset:64 sc1
	global_load_dword v162, v[146:147], off offset:128 sc1
	global_load_dword v163, v[148:149], off offset:128 sc1
	global_load_dword v164, v[146:147], off offset:192 sc1
	global_load_dword v165, v[148:149], off offset:192 sc1
	global_load_dword v166, v[146:147], off offset:512 sc1
	global_load_dword v167, v[148:149], off offset:512 sc1
	global_load_dword v168, v[146:147], off offset:576 sc1
	global_load_dword v169, v[148:149], off offset:576 sc1
	global_load_dword v170, v[146:147], off offset:640 sc1
	global_load_dword v171, v[148:149], off offset:640 sc1
	global_load_dword v172, v[146:147], off offset:704 sc1
	global_load_dword v173, v[148:149], off offset:704 sc1
	v_lshl_add_u64 v[146:147], s[16:17], 0, v[228:229]
	v_lshl_add_u64 v[146:147], v[210:211], 2, v[146:147]
	s_nop 0
	s_or_b32 s0, s8, s59
	v_or_b32_e32 v152, s0, v242
	v_cmp_eq_u32_e64 s[6:7], 0, v152
	s_and_saveexec_b64 s[0:1], s[6:7]
	s_cbranch_execz .LBB0_1424
	s_waitcnt vmcnt(14)
	v_fmamk_f32 v151, v158, 0x3a800000, v240
	v_mul_f32_e32 v152, 0x4f800000, v151
	v_cmp_gt_f32_e32 vcc, s68, v151
	s_nop 1
	v_cndmask_b32_e32 v151, v151, v152, vcc
	v_sqrt_f32_e32 v152, v151
	s_nop 0
	v_add_u32_e32 v153, -1, v152
	v_fma_f32 v155, -v153, v152, v151
	v_add_u32_e32 v154, 1, v152
	v_cmp_ge_f32_e64 s[8:9], 0, v155
	s_nop 1
	v_cndmask_b32_e64 v153, v152, v153, s[8:9]
	v_fma_f32 v152, -v154, v152, v151
	v_cmp_lt_f32_e64 s[8:9], 0, v152
	s_nop 1
	v_cndmask_b32_e64 v152, v153, v154, s[8:9]
	v_mul_f32_e32 v153, 0x37800000, v152
	v_cndmask_b32_e32 v152, v152, v153, vcc
	v_cmp_class_f32_e32 vcc, v151, v241
	s_nop 1
	v_cndmask_b32_e32 v151, v152, v151, vcc
	v_div_scale_f32 v152, s[2:3], v151, v151, 1.0
	v_rcp_f32_e32 v153, v152
	s_nop 0
	v_fma_f32 v154, -v152, v153, 1.0
	v_fmac_f32_e32 v153, v154, v153
	v_div_scale_f32 v154, vcc, 1.0, v151, 1.0
	v_mul_f32_e32 v155, v154, v153
	v_fma_f32 v156, -v152, v155, v154
	v_fmac_f32_e32 v155, v156, v153
	v_fma_f32 v152, -v152, v155, v154
	v_div_fmas_f32 v152, v152, v153, v155
	v_div_fixup_f32 v151, v152, v151, 1.0
	v_mul_f32_e32 v151, v151, v159
	v_mul_f32_e32 v151, 0x3c010204, v151
	v_lshl_add_u64 v[152:153], v[224:225], 2, s[26:27]
	global_store_dword v[152:153], v151, off
.LBB0_1424:
	s_or_b64 exec, exec, s[0:1]
	s_waitcnt vmcnt(14)
	global_store_dwordx4 v[146:147], v[94:97], off
	global_store_dwordx4 v[146:147], v[90:93], off offset:16
	global_store_dwordx4 v[146:147], v[86:89], off offset:512
	global_store_dwordx4 v[146:147], v[82:85], off offset:528
	v_div_scale_f32 v151, s[0:1], v159, v159, s69
	v_rcp_f32_e32 v152, v151
	v_div_scale_f32 v153, vcc, s69, v159, s69
	v_pk_mul_f32 v[96:97], v[96:97], v[16:17]
	v_fma_f32 v154, -v151, v152, 1.0
	v_fmac_f32_e32 v152, v154, v152
	v_mul_f32_e32 v154, v153, v152
	v_fma_f32 v155, -v151, v154, v153
	v_fmac_f32_e32 v154, v155, v152
	v_fma_f32 v151, -v151, v154, v153
	v_div_fmas_f32 v151, v151, v152, v154
	v_div_fixup_f32 v151, v151, v159, s69
	v_cmp_lt_f32_e32 vcc, 0, v159
	v_pk_mul_f32 v[94:95], v[94:95], v[14:15]
	v_pk_mul_f32 v[92:93], v[92:93], v[12:13]
	v_cndmask_b32_e32 v150, 0, v151, vcc
	v_pk_mul_f32 v[90:91], v[90:91], v[10:11]
	v_pk_fma_f32 v[94:95], v[94:95], v[150:151], s[34:35] op_sel_hi:[1,0,0]
	v_pk_fma_f32 v[96:97], v[96:97], v[150:151], s[34:35] op_sel_hi:[1,0,0]
	v_pk_fma_f32 v[90:91], v[90:91], v[150:151], s[34:35] op_sel_hi:[1,0,0]
	v_pk_fma_f32 v[92:93], v[92:93], v[150:151], s[34:35] op_sel_hi:[1,0,0]
	v_pk_mul_f32 v[88:89], v[88:89], v[8:9]
	v_pk_mul_f32 v[86:87], v[86:87], v[6:7]
	v_pk_mul_f32 v[84:85], v[84:85], v[4:5]
	v_pk_mul_f32 v[82:83], v[82:83], v[2:3]
	v_lshlrev_b32_e32 v95, 8, v95
	v_lshlrev_b32_e32 v96, 16, v96
	v_lshlrev_b32_e32 v91, 8, v91
	v_lshlrev_b32_e32 v92, 16, v92
	v_pk_fma_f32 v[86:87], v[86:87], v[150:151], s[34:35] op_sel_hi:[1,0,0]
	v_pk_fma_f32 v[88:89], v[88:89], v[150:151], s[34:35] op_sel_hi:[1,0,0]
	v_pk_fma_f32 v[82:83], v[82:83], v[150:151], s[34:35] op_sel_hi:[1,0,0]
	v_pk_fma_f32 v[84:85], v[84:85], v[150:151], s[34:35] op_sel_hi:[1,0,0]
	v_lshlrev_b64 v[152:153], 10, v[224:225]
	v_and_b32_e32 v95, 0xff00, v95
	v_and_b32_e32 v96, 0xff0000, v96
	v_perm_b32 v94, v97, v94, s70
	v_and_b32_e32 v91, 0xff00, v91
	v_and_b32_e32 v92, 0xff0000, v92
	v_perm_b32 v90, v93, v90, s70
	v_lshlrev_b32_e32 v87, 8, v87
	v_lshlrev_b32_e32 v88, 16, v88
	v_lshlrev_b32_e32 v83, 8, v83
	v_lshlrev_b32_e32 v84, 16, v84
	v_or3_b32 v94, v94, v95, v96
	v_or3_b32 v95, v90, v91, v92
	v_lshl_add_u64 v[90:91], s[18:19], 0, v[152:153]
	v_and_b32_e32 v87, 0xff00, v87
	v_and_b32_e32 v88, 0xff0000, v88
	v_perm_b32 v86, v89, v86, s70
	v_and_b32_e32 v83, 0xff00, v83
	v_and_b32_e32 v84, 0xff0000, v84
	v_perm_b32 v82, v85, v82, s70
	v_lshl_add_u64 v[90:91], v[90:91], 0, v[210:211]
	v_or3_b32 v86, v86, v87, v88
	v_or3_b32 v87, v82, v83, v84
	global_store_dwordx2 v[90:91], v[94:95], off
	global_store_dwordx2 v[90:91], v[86:87], off offset:128
	s_and_saveexec_b64 s[0:1], s[6:7]
	s_cbranch_execz .LBB0_1426
	s_waitcnt vmcnt(18)
	v_fmamk_f32 v83, v160, 0x3a800000, v240
	v_mul_f32_e32 v84, 0x4f800000, v83
	v_cmp_gt_f32_e32 vcc, s68, v83
	s_nop 1
	v_cndmask_b32_e32 v83, v83, v84, vcc
	v_sqrt_f32_e32 v84, v83
	s_nop 0
	v_add_u32_e32 v85, -1, v84
	v_fma_f32 v87, -v85, v84, v83
	v_add_u32_e32 v86, 1, v84
	v_cmp_ge_f32_e64 s[8:9], 0, v87
	s_nop 1
	v_cndmask_b32_e64 v85, v84, v85, s[8:9]
	v_fma_f32 v84, -v86, v84, v83
	v_cmp_lt_f32_e64 s[8:9], 0, v84
	s_nop 1
	v_cndmask_b32_e64 v84, v85, v86, s[8:9]
	v_mul_f32_e32 v85, 0x37800000, v84
	v_cndmask_b32_e32 v84, v84, v85, vcc
	v_cmp_class_f32_e32 vcc, v83, v241
	s_nop 1
	v_cndmask_b32_e32 v83, v84, v83, vcc
	v_div_scale_f32 v84, s[2:3], v83, v83, 1.0
	v_rcp_f32_e32 v85, v84
	s_nop 0
	v_fma_f32 v86, -v84, v85, 1.0
	v_fmac_f32_e32 v85, v86, v85
	v_div_scale_f32 v86, vcc, 1.0, v83, 1.0
	v_mul_f32_e32 v87, v86, v85
	v_fma_f32 v88, -v84, v87, v86
	v_fmac_f32_e32 v87, v88, v85
	v_fma_f32 v84, -v84, v87, v86
	v_div_fmas_f32 v84, v84, v85, v87
	v_div_fixup_f32 v83, v84, v83, 1.0
	v_mul_f32_e32 v83, v83, v161
	v_mul_f32_e32 v83, 0x3c010204, v83
	v_lshl_add_u64 v[84:85], v[216:217], 2, s[26:27]
	global_store_dword v[84:85], v83, off
;     __device__ __forceinline__ void operator()(f32x4 (&acc)[2][2][4][2], const Unit& u, int wr, int wc, int fr, int fq) const {
;     ...
; #pragma unroll
;         for (int ai = 0; ai < 2; ++ai)
; #pragma unroll
;             for (int m = 0; m < 4; ++m) {
;                 const int row = row0 + ai * HALF + m * 16;
;                 const float ss = __hip_atomic_load(SS + row, __ATOMIC_RELAXED, __HIP_MEMORY_SCOPE_AGENT);
;                 const float rstd = 1.0f / sqrtf(ss * (1.f / 1024.f) + 1e-6f);
;                 float qs = 0.f;
;                 if constexpr (!FINAL) {
;                     const float am = __uint_as_float(__hip_atomic_load(AM + row, __ATOMIC_RELAXED, __HIP_MEMORY_SCOPE_AGENT));
;                     qs = am > 0.f ? 127.f / am : 0.f;
;                     if (u.pn == 0 && wc == 0 && fq == 0) SH[row] = am * rstd * (1.f / 127.f);
;                 }
; #pragma unroll
;                 for (int bj = 0; bj < 2; ++bj) {
;                     const size_t off = (size_t)row * 1024 + col0 + bj * HALF;
;                     const f32x4 y0 = acc[ai][bj][m][0] * rstd * gv[bj][0], y1 = acc[ai][bj][m][1] * rstd * gv[bj][1];
;                     if constexpr (FINAL) { *(f32x4*)(out + off) = y0; *(f32x4*)(out + off + 4) = y1; }
;                     else {
;                         u32x2 q8; q8.x = q8x4(acc[ai][bj][m][0] * gv[bj][0], qs); q8.y = q8x4(acc[ai][bj][m][1] * gv[bj][1], qs);
;                         *(u32x2*)(H8 + off) = q8;
;                     }
;                 }
.LBB0_1426:
	s_or_b64 exec, exec, s[0:1]
	s_waitcnt vmcnt(18)
	s_mov_b32 s98, 0x10000
	s_mov_b32 s99, 0
	v_lshl_add_u64 v[148:149], v[146:147], 0, s[98:99]
	global_store_dwordx4 v[148:149], v[110:113], off
	global_store_dwordx4 v[148:149], v[106:109], off offset:16
	global_store_dwordx4 v[148:149], v[102:105], off offset:512
	global_store_dwordx4 v[148:149], v[98:101], off offset:528
	v_div_scale_f32 v83, s[0:1], v161, v161, s69
	v_rcp_f32_e32 v84, v83
	v_div_scale_f32 v85, vcc, s69, v161, s69
	v_pk_mul_f32 v[88:89], v[110:111], v[14:15]
	v_fma_f32 v86, -v83, v84, 1.0
	v_fmac_f32_e32 v84, v86, v84
	v_mul_f32_e32 v86, v85, v84
	v_fma_f32 v87, -v83, v86, v85
	v_fmac_f32_e32 v86, v87, v84
	v_fma_f32 v83, -v83, v86, v85
	v_div_fmas_f32 v83, v83, v84, v86
	v_div_fixup_f32 v83, v83, v161, s69
	v_cmp_lt_f32_e32 vcc, 0, v161
	v_pk_mul_f32 v[86:87], v[112:113], v[16:17]
	v_pk_mul_f32 v[90:91], v[106:107], v[10:11]
	v_cndmask_b32_e32 v82, 0, v83, vcc
	v_pk_fma_f32 v[88:89], v[88:89], v[82:83], s[34:35] op_sel_hi:[1,0,0]
	v_pk_fma_f32 v[86:87], v[86:87], v[82:83], s[34:35] op_sel_hi:[1,0,0]
	v_lshlrev_b32_e32 v83, 8, v89
	v_and_b32_e32 v83, 0xff00, v83
	v_lshlrev_b32_e32 v86, 16, v86
	v_perm_b32 v87, v87, v88, s70
	v_pk_mul_f32 v[88:89], v[108:109], v[12:13]
	v_and_b32_e32 v86, 0xff0000, v86
	v_pk_fma_f32 v[90:91], v[90:91], v[82:83], s[34:35] op_sel_hi:[1,0,0]
	v_pk_fma_f32 v[88:89], v[88:89], v[82:83], s[34:35] op_sel_hi:[1,0,0]
	v_lshlrev_b64 v[84:85], 10, v[216:217]
	v_or3_b32 v86, v87, v83, v86
	v_lshlrev_b32_e32 v83, 8, v91
	v_lshlrev_b32_e32 v87, 16, v88
	v_and_b32_e32 v83, 0xff00, v83
	v_and_b32_e32 v87, 0xff0000, v87
	v_perm_b32 v88, v89, v90, s70
	v_lshl_add_u64 v[84:85], s[18:19], 0, v[84:85]
	v_or3_b32 v87, v88, v83, v87
	v_lshl_add_u64 v[84:85], v[84:85], 0, v[210:211]
	global_store_dwordx2 v[84:85], v[86:87], off
	v_pk_mul_f32 v[86:87], v[104:105], v[8:9]
	v_pk_mul_f32 v[88:89], v[102:103], v[6:7]
	v_pk_fma_f32 v[86:87], v[86:87], v[82:83], s[34:35] op_sel_hi:[1,0,0]
	v_pk_fma_f32 v[88:89], v[88:89], v[82:83], s[34:35] op_sel_hi:[1,0,0]
	v_lshlrev_b32_e32 v86, 16, v86
	v_lshlrev_b32_e32 v83, 8, v89
	v_and_b32_e32 v83, 0xff00, v83
	v_and_b32_e32 v86, 0xff0000, v86
	v_perm_b32 v87, v87, v88, s70
	v_pk_mul_f32 v[88:89], v[100:101], v[4:5]
	v_pk_mul_f32 v[90:91], v[98:99], v[2:3]
	v_or3_b32 v86, v87, v83, v86
	v_pk_fma_f32 v[90:91], v[90:91], v[82:83], s[34:35] op_sel_hi:[1,0,0]
	v_pk_fma_f32 v[82:83], v[88:89], v[82:83], s[34:35] op_sel_hi:[1,0,0]
	v_lshlrev_b32_e32 v87, 8, v91
	v_lshlrev_b32_e32 v82, 16, v82
	v_and_b32_e32 v87, 0xff00, v87
	v_and_b32_e32 v82, 0xff0000, v82
	v_perm_b32 v83, v83, v90, s70
	v_or3_b32 v87, v83, v87, v82
	global_store_dwordx2 v[84:85], v[86:87], off offset:128
	s_and_saveexec_b64 s[0:1], s[6:7]
	s_cbranch_execz .LBB0_1428
	s_waitcnt vmcnt(22)
	v_fmamk_f32 v83, v162, 0x3a800000, v240
	v_mul_f32_e32 v84, 0x4f800000, v83
	v_cmp_gt_f32_e32 vcc, s68, v83
	s_nop 1
	v_cndmask_b32_e32 v83, v83, v84, vcc
	v_sqrt_f32_e32 v84, v83
	s_nop 0
	v_add_u32_e32 v85, -1, v84
	v_fma_f32 v87, -v85, v84, v83
	v_add_u32_e32 v86, 1, v84
	v_cmp_ge_f32_e64 s[8:9], 0, v87
	s_nop 1
	v_cndmask_b32_e64 v85, v84, v85, s[8:9]
	v_fma_f32 v84, -v86, v84, v83
	v_cmp_lt_f32_e64 s[8:9], 0, v84
	s_nop 1
	v_cndmask_b32_e64 v84, v85, v86, s[8:9]
	v_mul_f32_e32 v85, 0x37800000, v84
	v_cndmask_b32_e32 v84, v84, v85, vcc
	v_cmp_class_f32_e32 vcc, v83, v241
	s_nop 1
	v_cndmask_b32_e32 v83, v84, v83, vcc
	v_div_scale_f32 v84, s[2:3], v83, v83, 1.0
	v_rcp_f32_e32 v85, v84
	s_nop 0
	v_fma_f32 v86, -v84, v85, 1.0
	v_fmac_f32_e32 v85, v86, v85
	v_div_scale_f32 v86, vcc, 1.0, v83, 1.0
	v_mul_f32_e32 v87, v86, v85
	v_fma_f32 v88, -v84, v87, v86
	v_fmac_f32_e32 v87, v88, v85
	v_fma_f32 v84, -v84, v87, v86
	v_div_fmas_f32 v84, v84, v85, v87
	v_div_fixup_f32 v83, v84, v83, 1.0
	v_mul_f32_e32 v83, v83, v163
	v_mul_f32_e32 v83, 0x3c010204, v83
	v_lshl_add_u64 v[84:85], v[212:213], 2, s[26:27]
	global_store_dword v[84:85], v83, off
.LBB0_1428:
	s_or_b64 exec, exec, s[0:1]
	s_waitcnt vmcnt(22)
	s_mov_b32 s98, 0x20000
	s_mov_b32 s99, 0
	v_lshl_add_u64 v[148:149], v[146:147], 0, s[98:99]
	global_store_dwordx4 v[148:149], v[130:133], off
	global_store_dwordx4 v[148:149], v[122:125], off offset:16
	global_store_dwordx4 v[148:149], v[118:121], off offset:512
	global_store_dwordx4 v[148:149], v[114:117], off offset:528
	v_div_scale_f32 v83, s[0:1], v163, v163, s69
	v_rcp_f32_e32 v84, v83
	v_div_scale_f32 v85, vcc, s69, v163, s69
	v_pk_mul_f32 v[88:89], v[130:131], v[14:15]
	v_fma_f32 v86, -v83, v84, 1.0
	v_fmac_f32_e32 v84, v86, v84
	v_mul_f32_e32 v86, v85, v84
	v_fma_f32 v87, -v83, v86, v85
	v_fmac_f32_e32 v86, v87, v84
	v_fma_f32 v83, -v83, v86, v85
	v_div_fmas_f32 v83, v83, v84, v86
	v_div_fixup_f32 v83, v83, v163, s69
	v_cmp_lt_f32_e32 vcc, 0, v163
	v_pk_mul_f32 v[86:87], v[132:133], v[16:17]
	v_pk_mul_f32 v[90:91], v[122:123], v[10:11]
	v_cndmask_b32_e32 v82, 0, v83, vcc
	v_pk_fma_f32 v[88:89], v[88:89], v[82:83], s[34:35] op_sel_hi:[1,0,0]
	v_pk_fma_f32 v[86:87], v[86:87], v[82:83], s[34:35] op_sel_hi:[1,0,0]
	v_lshlrev_b32_e32 v83, 8, v89
	v_and_b32_e32 v83, 0xff00, v83
	v_lshlrev_b32_e32 v86, 16, v86
	v_perm_b32 v87, v87, v88, s70
	v_pk_mul_f32 v[88:89], v[124:125], v[12:13]
	v_and_b32_e32 v86, 0xff0000, v86
	v_pk_fma_f32 v[90:91], v[90:91], v[82:83], s[34:35] op_sel_hi:[1,0,0]
	v_pk_fma_f32 v[88:89], v[88:89], v[82:83], s[34:35] op_sel_hi:[1,0,0]
	v_lshlrev_b64 v[84:85], 10, v[212:213]
	v_or3_b32 v86, v87, v83, v86
	v_lshlrev_b32_e32 v83, 8, v91
	v_lshlrev_b32_e32 v87, 16, v88
	v_and_b32_e32 v83, 0xff00, v83
	v_and_b32_e32 v87, 0xff0000, v87
	v_perm_b32 v88, v89, v90, s70
	v_lshl_add_u64 v[84:85], s[18:19], 0, v[84:85]
	v_or3_b32 v87, v88, v83, v87
	v_lshl_add_u64 v[84:85], v[84:85], 0, v[210:211]
	global_store_dwordx2 v[84:85], v[86:87], off
	v_pk_mul_f32 v[86:87], v[120:121], v[8:9]
	v_pk_mul_f32 v[88:89], v[118:119], v[6:7]
	v_pk_fma_f32 v[86:87], v[86:87], v[82:83], s[34:35] op_sel_hi:[1,0,0]
	v_pk_fma_f32 v[88:89], v[88:89], v[82:83], s[34:35] op_sel_hi:[1,0,0]
	v_lshlrev_b32_e32 v86, 16, v86
	v_lshlrev_b32_e32 v83, 8, v89
	v_and_b32_e32 v83, 0xff00, v83
	v_and_b32_e32 v86, 0xff0000, v86
	v_perm_b32 v87, v87, v88, s70
	v_pk_mul_f32 v[88:89], v[116:117], v[4:5]
	v_pk_mul_f32 v[90:91], v[114:115], v[2:3]
	v_or3_b32 v86, v87, v83, v86
	v_pk_fma_f32 v[90:91], v[90:91], v[82:83], s[34:35] op_sel_hi:[1,0,0]
	v_pk_fma_f32 v[82:83], v[88:89], v[82:83], s[34:35] op_sel_hi:[1,0,0]
	v_lshlrev_b32_e32 v87, 8, v91
	v_lshlrev_b32_e32 v82, 16, v82
	v_and_b32_e32 v87, 0xff00, v87
	v_and_b32_e32 v82, 0xff0000, v82
	v_perm_b32 v83, v83, v90, s70
	v_or3_b32 v87, v83, v87, v82
	global_store_dwordx2 v[84:85], v[86:87], off offset:128
	s_and_saveexec_b64 s[0:1], s[6:7]
	s_cbranch_execz .LBB0_1430
;     __device__ __forceinline__ void operator()(f32x4 (&acc)[2][2][4][2], const Unit& u, int wr, int wc, int fr, int fq) const {
;     ...
; #pragma unroll
;         for (int ai = 0; ai < 2; ++ai)
; #pragma unroll
;             for (int m = 0; m < 4; ++m) {
;                 const int row = row0 + ai * HALF + m * 16;
;                 const float ss = __hip_atomic_load(SS + row, __ATOMIC_RELAXED, __HIP_MEMORY_SCOPE_AGENT);
;                 const float rstd = 1.0f / sqrtf(ss * (1.f / 1024.f) + 1e-6f);
;                 float qs = 0.f;
;                 if constexpr (!FINAL) {
;                     const float am = __uint_as_float(__hip_atomic_load(AM + row, __ATOMIC_RELAXED, __HIP_MEMORY_SCOPE_AGENT));
;                     qs = am > 0.f ? 127.f / am : 0.f;
;                     if (u.pn == 0 && wc == 0 && fq == 0) SH[row] = am * rstd * (1.f / 127.f);
;                 }
; #pragma unroll
;                 for (int bj = 0; bj < 2; ++bj) {
;                     const size_t off = (size_t)row * 1024 + col0 + bj * HALF;
;                     const f32x4 y0 = acc[ai][bj][m][0] * rstd * gv[bj][0], y1 = acc[ai][bj][m][1] * rstd * gv[bj][1];
;                     if constexpr (FINAL) { *(f32x4*)(out + off) = y0; *(f32x4*)(out + off + 4) = y1; }
;                     else {
;                         u32x2 q8; q8.x = q8x4(acc[ai][bj][m][0] * gv[bj][0], qs); q8.y = q8x4(acc[ai][bj][m][1] * gv[bj][1], qs);
;                         *(u32x2*)(H8 + off) = q8;
;                     }
;                 }
	s_waitcnt vmcnt(26)
	v_fmamk_f32 v83, v164, 0x3a800000, v240
	v_mul_f32_e32 v84, 0x4f800000, v83
	v_cmp_gt_f32_e32 vcc, s68, v83
	s_nop 1
	v_cndmask_b32_e32 v83, v83, v84, vcc
	v_sqrt_f32_e32 v84, v83
	s_nop 0
	v_add_u32_e32 v85, -1, v84
	v_fma_f32 v87, -v85, v84, v83
	v_add_u32_e32 v86, 1, v84
	v_cmp_ge_f32_e64 s[8:9], 0, v87
	s_nop 1
	v_cndmask_b32_e64 v85, v84, v85, s[8:9]
	v_fma_f32 v84, -v86, v84, v83
	v_cmp_lt_f32_e64 s[8:9], 0, v84
	s_nop 1
	v_cndmask_b32_e64 v84, v85, v86, s[8:9]
	v_mul_f32_e32 v85, 0x37800000, v84
	v_cndmask_b32_e32 v84, v84, v85, vcc
	v_cmp_class_f32_e32 vcc, v83, v241
	s_nop 1
	v_cndmask_b32_e32 v83, v84, v83, vcc
	v_div_scale_f32 v84, s[2:3], v83, v83, 1.0
	v_rcp_f32_e32 v85, v84
	s_nop 0
	v_fma_f32 v86, -v84, v85, 1.0
	v_fmac_f32_e32 v85, v86, v85
	v_div_scale_f32 v86, vcc, 1.0, v83, 1.0
	v_mul_f32_e32 v87, v86, v85
	v_fma_f32 v88, -v84, v87, v86
	v_fmac_f32_e32 v87, v88, v85
	v_fma_f32 v84, -v84, v87, v86
	v_div_fmas_f32 v84, v84, v85, v87
	v_div_fixup_f32 v83, v84, v83, 1.0
	v_mul_f32_e32 v83, v83, v165
	v_mul_f32_e32 v83, 0x3c010204, v83
	v_lshl_add_u64 v[84:85], v[214:215], 2, s[26:27]
	global_store_dword v[84:85], v83, off
.LBB0_1430:
	s_or_b64 exec, exec, s[0:1]
	s_waitcnt vmcnt(26)
	s_mov_b32 s98, 0x30000
	s_mov_b32 s99, 0
	v_lshl_add_u64 v[148:149], v[146:147], 0, s[98:99]
	global_store_dwordx4 v[148:149], v[142:145], off
	global_store_dwordx4 v[148:149], v[138:141], off offset:16
	global_store_dwordx4 v[148:149], v[134:137], off offset:512
	global_store_dwordx4 v[148:149], v[126:129], off offset:528
	v_div_scale_f32 v83, s[0:1], v165, v165, s69
	v_rcp_f32_e32 v84, v83
	v_div_scale_f32 v85, vcc, s69, v165, s69
	v_pk_mul_f32 v[88:89], v[142:143], v[14:15]
	v_fma_f32 v86, -v83, v84, 1.0
	v_fmac_f32_e32 v84, v86, v84
	v_mul_f32_e32 v86, v85, v84
	v_fma_f32 v87, -v83, v86, v85
	v_fmac_f32_e32 v86, v87, v84
	v_fma_f32 v83, -v83, v86, v85
	v_div_fmas_f32 v83, v83, v84, v86
	v_div_fixup_f32 v83, v83, v165, s69
	v_cmp_lt_f32_e32 vcc, 0, v165
	v_pk_mul_f32 v[86:87], v[144:145], v[16:17]
	v_pk_mul_f32 v[90:91], v[138:139], v[10:11]
	v_cndmask_b32_e32 v82, 0, v83, vcc
	v_pk_fma_f32 v[88:89], v[88:89], v[82:83], s[34:35] op_sel_hi:[1,0,0]
	v_pk_fma_f32 v[86:87], v[86:87], v[82:83], s[34:35] op_sel_hi:[1,0,0]
	v_lshlrev_b32_e32 v83, 8, v89
	v_and_b32_e32 v83, 0xff00, v83
	v_lshlrev_b32_e32 v86, 16, v86
	v_perm_b32 v87, v87, v88, s70
	v_pk_mul_f32 v[88:89], v[140:141], v[12:13]
	v_and_b32_e32 v86, 0xff0000, v86
	v_pk_fma_f32 v[90:91], v[90:91], v[82:83], s[34:35] op_sel_hi:[1,0,0]
	v_pk_fma_f32 v[88:89], v[88:89], v[82:83], s[34:35] op_sel_hi:[1,0,0]
	v_lshlrev_b64 v[84:85], 10, v[214:215]
	v_or3_b32 v86, v87, v83, v86
	v_lshlrev_b32_e32 v83, 8, v91
	v_lshlrev_b32_e32 v87, 16, v88
	v_and_b32_e32 v83, 0xff00, v83
	v_and_b32_e32 v87, 0xff0000, v87
	v_perm_b32 v88, v89, v90, s70
	v_lshl_add_u64 v[84:85], s[18:19], 0, v[84:85]
	v_or3_b32 v87, v88, v83, v87
	v_lshl_add_u64 v[84:85], v[84:85], 0, v[210:211]
	global_store_dwordx2 v[84:85], v[86:87], off
	v_pk_mul_f32 v[86:87], v[136:137], v[8:9]
	v_pk_mul_f32 v[88:89], v[134:135], v[6:7]
	v_pk_fma_f32 v[86:87], v[86:87], v[82:83], s[34:35] op_sel_hi:[1,0,0]
	v_pk_fma_f32 v[88:89], v[88:89], v[82:83], s[34:35] op_sel_hi:[1,0,0]
	v_lshlrev_b32_e32 v86, 16, v86
	v_lshlrev_b32_e32 v83, 8, v89
	v_and_b32_e32 v83, 0xff00, v83
	v_and_b32_e32 v86, 0xff0000, v86
	v_perm_b32 v87, v87, v88, s70
	v_pk_mul_f32 v[88:89], v[128:129], v[4:5]
	v_pk_mul_f32 v[90:91], v[126:127], v[2:3]
	v_or3_b32 v86, v87, v83, v86
	v_pk_fma_f32 v[90:91], v[90:91], v[82:83], s[34:35] op_sel_hi:[1,0,0]
	v_pk_fma_f32 v[82:83], v[88:89], v[82:83], s[34:35] op_sel_hi:[1,0,0]
	v_lshlrev_b32_e32 v87, 8, v91
	v_lshlrev_b32_e32 v82, 16, v82
	v_and_b32_e32 v87, 0xff00, v87
	v_and_b32_e32 v82, 0xff0000, v82
	v_perm_b32 v83, v83, v90, s70
	v_or3_b32 v87, v83, v87, v82
	global_store_dwordx2 v[84:85], v[86:87], off offset:128
	s_and_saveexec_b64 s[0:1], s[6:7]
	s_cbranch_execz .LBB0_1432
	s_waitcnt vmcnt(30)
	v_fmamk_f32 v83, v166, 0x3a800000, v240
	v_mul_f32_e32 v84, 0x4f800000, v83
	v_cmp_gt_f32_e32 vcc, s68, v83
	s_nop 1
	v_cndmask_b32_e32 v83, v83, v84, vcc
	v_sqrt_f32_e32 v84, v83
	s_nop 0
	v_add_u32_e32 v85, -1, v84
	v_fma_f32 v87, -v85, v84, v83
	v_add_u32_e32 v86, 1, v84
	v_cmp_ge_f32_e64 s[8:9], 0, v87
	s_nop 1
	v_cndmask_b32_e64 v85, v84, v85, s[8:9]
	v_fma_f32 v84, -v86, v84, v83
	v_cmp_lt_f32_e64 s[8:9], 0, v84
	s_nop 1
	v_cndmask_b32_e64 v84, v85, v86, s[8:9]
	v_mul_f32_e32 v85, 0x37800000, v84
	v_cndmask_b32_e32 v84, v84, v85, vcc
	v_cmp_class_f32_e32 vcc, v83, v241
	s_nop 1
	v_cndmask_b32_e32 v83, v84, v83, vcc
	v_div_scale_f32 v84, s[2:3], v83, v83, 1.0
	v_rcp_f32_e32 v85, v84
	s_nop 0
	v_fma_f32 v86, -v84, v85, 1.0
	v_fmac_f32_e32 v85, v86, v85
	v_div_scale_f32 v86, vcc, 1.0, v83, 1.0
	v_mul_f32_e32 v87, v86, v85
	v_fma_f32 v88, -v84, v87, v86
	v_fmac_f32_e32 v87, v88, v85
	v_fma_f32 v84, -v84, v87, v86
	v_div_fmas_f32 v84, v84, v85, v87
	v_div_fixup_f32 v83, v84, v83, 1.0
	v_mul_f32_e32 v83, v83, v167
	v_mul_f32_e32 v83, 0x3c010204, v83
	v_lshl_add_u64 v[84:85], v[218:219], 2, s[26:27]
	global_store_dword v[84:85], v83, off
;     __device__ __forceinline__ void operator()(f32x4 (&acc)[2][2][4][2], const Unit& u, int wr, int wc, int fr, int fq) const {
;     ...
; #pragma unroll
;         for (int ai = 0; ai < 2; ++ai)
; #pragma unroll
;             for (int m = 0; m < 4; ++m) {
;                 const int row = row0 + ai * HALF + m * 16;
;                 const float ss = __hip_atomic_load(SS + row, __ATOMIC_RELAXED, __HIP_MEMORY_SCOPE_AGENT);
;                 const float rstd = 1.0f / sqrtf(ss * (1.f / 1024.f) + 1e-6f);
;                 float qs = 0.f;
;                 if constexpr (!FINAL) {
;                     const float am = __uint_as_float(__hip_atomic_load(AM + row, __ATOMIC_RELAXED, __HIP_MEMORY_SCOPE_AGENT));
;                     qs = am > 0.f ? 127.f / am : 0.f;
;                     if (u.pn == 0 && wc == 0 && fq == 0) SH[row] = am * rstd * (1.f / 127.f);
;                 }
; #pragma unroll
;                 for (int bj = 0; bj < 2; ++bj) {
;                     const size_t off = (size_t)row * 1024 + col0 + bj * HALF;
;                     const f32x4 y0 = acc[ai][bj][m][0] * rstd * gv[bj][0], y1 = acc[ai][bj][m][1] * rstd * gv[bj][1];
;                     if constexpr (FINAL) { *(f32x4*)(out + off) = y0; *(f32x4*)(out + off + 4) = y1; }
;                     else {
;                         u32x2 q8; q8.x = q8x4(acc[ai][bj][m][0] * gv[bj][0], qs); q8.y = q8x4(acc[ai][bj][m][1] * gv[bj][1], qs);
;                         *(u32x2*)(H8 + off) = q8;
;                     }
;                 }
.LBB0_1432:
	s_or_b64 exec, exec, s[0:1]
	s_waitcnt vmcnt(30)
	s_mov_b32 s98, 0x80000
	s_mov_b32 s99, 0
	v_lshl_add_u64 v[148:149], v[146:147], 0, s[98:99]
	global_store_dwordx4 v[148:149], v[78:81], off
	global_store_dwordx4 v[148:149], v[74:77], off offset:16
	global_store_dwordx4 v[148:149], v[70:73], off offset:512
	global_store_dwordx4 v[148:149], v[66:69], off offset:528
	v_div_scale_f32 v83, s[0:1], v167, v167, s69
	v_rcp_f32_e32 v84, v83
	v_div_scale_f32 v85, vcc, s69, v167, s69
	v_pk_mul_f32 v[80:81], v[80:81], v[16:17]
	v_fma_f32 v86, -v83, v84, 1.0
	v_fmac_f32_e32 v84, v86, v84
	v_mul_f32_e32 v86, v85, v84
	v_fma_f32 v87, -v83, v86, v85
	v_fmac_f32_e32 v86, v87, v84
	v_fma_f32 v83, -v83, v86, v85
	v_div_fmas_f32 v83, v83, v84, v86
	v_div_fixup_f32 v83, v83, v167, s69
	v_cmp_lt_f32_e32 vcc, 0, v167
	v_pk_mul_f32 v[78:79], v[78:79], v[14:15]
	v_pk_mul_f32 v[76:77], v[76:77], v[12:13]
	v_cndmask_b32_e32 v82, 0, v83, vcc
	v_pk_mul_f32 v[74:75], v[74:75], v[10:11]
	v_pk_fma_f32 v[78:79], v[78:79], v[82:83], s[34:35] op_sel_hi:[1,0,0]
	v_pk_fma_f32 v[80:81], v[80:81], v[82:83], s[34:35] op_sel_hi:[1,0,0]
	v_pk_fma_f32 v[74:75], v[74:75], v[82:83], s[34:35] op_sel_hi:[1,0,0]
	v_pk_fma_f32 v[76:77], v[76:77], v[82:83], s[34:35] op_sel_hi:[1,0,0]
	v_pk_mul_f32 v[72:73], v[72:73], v[8:9]
	v_pk_mul_f32 v[70:71], v[70:71], v[6:7]
	v_pk_mul_f32 v[68:69], v[68:69], v[4:5]
	v_pk_mul_f32 v[66:67], v[66:67], v[2:3]
	v_lshlrev_b32_e32 v79, 8, v79
	v_lshlrev_b32_e32 v80, 16, v80
	v_lshlrev_b32_e32 v75, 8, v75
	v_lshlrev_b32_e32 v76, 16, v76
	v_pk_fma_f32 v[70:71], v[70:71], v[82:83], s[34:35] op_sel_hi:[1,0,0]
	v_pk_fma_f32 v[72:73], v[72:73], v[82:83], s[34:35] op_sel_hi:[1,0,0]
	v_pk_fma_f32 v[66:67], v[66:67], v[82:83], s[34:35] op_sel_hi:[1,0,0]
	v_pk_fma_f32 v[68:69], v[68:69], v[82:83], s[34:35] op_sel_hi:[1,0,0]
	v_lshlrev_b64 v[84:85], 10, v[218:219]
	v_and_b32_e32 v79, 0xff00, v79
	v_and_b32_e32 v80, 0xff0000, v80
	v_perm_b32 v78, v81, v78, s70
	v_and_b32_e32 v75, 0xff00, v75
	v_and_b32_e32 v76, 0xff0000, v76
	v_perm_b32 v74, v77, v74, s70
	v_lshlrev_b32_e32 v71, 8, v71
	v_lshlrev_b32_e32 v72, 16, v72
	v_lshlrev_b32_e32 v67, 8, v67
	v_lshlrev_b32_e32 v68, 16, v68
	v_or3_b32 v78, v78, v79, v80
	v_or3_b32 v79, v74, v75, v76
	v_lshl_add_u64 v[74:75], s[18:19], 0, v[84:85]
	v_and_b32_e32 v71, 0xff00, v71
	v_and_b32_e32 v72, 0xff0000, v72
	v_perm_b32 v70, v73, v70, s70
	v_and_b32_e32 v67, 0xff00, v67
	v_and_b32_e32 v68, 0xff0000, v68
	v_perm_b32 v66, v69, v66, s70
	v_lshl_add_u64 v[74:75], v[74:75], 0, v[210:211]
	v_or3_b32 v70, v70, v71, v72
	v_or3_b32 v71, v66, v67, v68
	global_store_dwordx2 v[74:75], v[78:79], off
	global_store_dwordx2 v[74:75], v[70:71], off offset:128
	s_and_saveexec_b64 s[0:1], s[6:7]
	s_cbranch_execz .LBB0_1434
	s_waitcnt vmcnt(34)
	v_fmamk_f32 v67, v168, 0x3a800000, v240
	v_mul_f32_e32 v68, 0x4f800000, v67
	v_cmp_gt_f32_e32 vcc, s68, v67
	s_nop 1
	v_cndmask_b32_e32 v67, v67, v68, vcc
	v_sqrt_f32_e32 v68, v67
	s_nop 0
	v_add_u32_e32 v69, -1, v68
	v_fma_f32 v71, -v69, v68, v67
	v_add_u32_e32 v70, 1, v68
	v_cmp_ge_f32_e64 s[8:9], 0, v71
	s_nop 1
	v_cndmask_b32_e64 v69, v68, v69, s[8:9]
	v_fma_f32 v68, -v70, v68, v67
	v_cmp_lt_f32_e64 s[8:9], 0, v68
	s_nop 1
	v_cndmask_b32_e64 v68, v69, v70, s[8:9]
	v_mul_f32_e32 v69, 0x37800000, v68
	v_cndmask_b32_e32 v68, v68, v69, vcc
	v_cmp_class_f32_e32 vcc, v67, v241
	s_nop 1
	v_cndmask_b32_e32 v67, v68, v67, vcc
	v_div_scale_f32 v68, s[2:3], v67, v67, 1.0
	v_rcp_f32_e32 v69, v68
	s_nop 0
	v_fma_f32 v70, -v68, v69, 1.0
	v_fmac_f32_e32 v69, v70, v69
	v_div_scale_f32 v70, vcc, 1.0, v67, 1.0
	v_mul_f32_e32 v71, v70, v69
	v_fma_f32 v72, -v68, v71, v70
	v_fmac_f32_e32 v71, v72, v69
	v_fma_f32 v68, -v68, v71, v70
	v_div_fmas_f32 v68, v68, v69, v71
	v_div_fixup_f32 v67, v68, v67, 1.0
	v_mul_f32_e32 v67, v67, v169
	v_mul_f32_e32 v67, 0x3c010204, v67
	v_lshl_add_u64 v[68:69], v[220:221], 2, s[26:27]
	global_store_dword v[68:69], v67, off
.LBB0_1434:
	s_or_b64 exec, exec, s[0:1]
	s_waitcnt vmcnt(34)
	s_mov_b32 s98, 0x90000
	s_mov_b32 s99, 0
	v_lshl_add_u64 v[148:149], v[146:147], 0, s[98:99]
	global_store_dwordx4 v[148:149], v[62:65], off
	global_store_dwordx4 v[148:149], v[58:61], off offset:16
	global_store_dwordx4 v[148:149], v[54:57], off offset:512
	global_store_dwordx4 v[148:149], v[50:53], off offset:528
	v_div_scale_f32 v67, s[0:1], v169, v169, s69
	v_rcp_f32_e32 v68, v67
	v_div_scale_f32 v69, vcc, s69, v169, s69
	v_pk_mul_f32 v[64:65], v[64:65], v[16:17]
	v_fma_f32 v70, -v67, v68, 1.0
	v_fmac_f32_e32 v68, v70, v68
	v_mul_f32_e32 v70, v69, v68
	v_fma_f32 v71, -v67, v70, v69
	v_fmac_f32_e32 v70, v71, v68
	v_fma_f32 v67, -v67, v70, v69
	v_div_fmas_f32 v67, v67, v68, v70
	v_div_fixup_f32 v67, v67, v169, s69
	v_cmp_lt_f32_e32 vcc, 0, v169
	v_pk_mul_f32 v[62:63], v[62:63], v[14:15]
	v_pk_mul_f32 v[60:61], v[60:61], v[12:13]
	v_cndmask_b32_e32 v66, 0, v67, vcc
	v_pk_mul_f32 v[58:59], v[58:59], v[10:11]
	v_pk_fma_f32 v[62:63], v[62:63], v[66:67], s[34:35] op_sel_hi:[1,0,0]
	v_pk_fma_f32 v[64:65], v[64:65], v[66:67], s[34:35] op_sel_hi:[1,0,0]
	v_pk_fma_f32 v[58:59], v[58:59], v[66:67], s[34:35] op_sel_hi:[1,0,0]
	v_pk_fma_f32 v[60:61], v[60:61], v[66:67], s[34:35] op_sel_hi:[1,0,0]
	v_pk_mul_f32 v[56:57], v[56:57], v[8:9]
	v_pk_mul_f32 v[54:55], v[54:55], v[6:7]
	v_pk_mul_f32 v[52:53], v[52:53], v[4:5]
	v_pk_mul_f32 v[50:51], v[50:51], v[2:3]
	v_lshlrev_b32_e32 v63, 8, v63
	v_lshlrev_b32_e32 v64, 16, v64
	v_lshlrev_b32_e32 v59, 8, v59
	v_lshlrev_b32_e32 v60, 16, v60
	v_pk_fma_f32 v[54:55], v[54:55], v[66:67], s[34:35] op_sel_hi:[1,0,0]
	v_pk_fma_f32 v[56:57], v[56:57], v[66:67], s[34:35] op_sel_hi:[1,0,0]
	v_pk_fma_f32 v[50:51], v[50:51], v[66:67], s[34:35] op_sel_hi:[1,0,0]
	v_pk_fma_f32 v[52:53], v[52:53], v[66:67], s[34:35] op_sel_hi:[1,0,0]
	v_lshlrev_b64 v[68:69], 10, v[220:221]
	v_and_b32_e32 v63, 0xff00, v63
	v_and_b32_e32 v64, 0xff0000, v64
	v_perm_b32 v62, v65, v62, s70
	v_and_b32_e32 v59, 0xff00, v59
	v_and_b32_e32 v60, 0xff0000, v60
	v_perm_b32 v58, v61, v58, s70
	v_lshlrev_b32_e32 v55, 8, v55
	v_lshlrev_b32_e32 v56, 16, v56
	v_lshlrev_b32_e32 v51, 8, v51
	v_lshlrev_b32_e32 v52, 16, v52
	v_or3_b32 v62, v62, v63, v64
	v_or3_b32 v63, v58, v59, v60
	v_lshl_add_u64 v[58:59], s[18:19], 0, v[68:69]
	v_and_b32_e32 v55, 0xff00, v55
	v_and_b32_e32 v56, 0xff0000, v56
	v_perm_b32 v54, v57, v54, s70
	v_and_b32_e32 v51, 0xff00, v51
	v_and_b32_e32 v52, 0xff0000, v52
	v_perm_b32 v50, v53, v50, s70
	v_lshl_add_u64 v[58:59], v[58:59], 0, v[210:211]
	v_or3_b32 v54, v54, v55, v56
	v_or3_b32 v55, v50, v51, v52
	global_store_dwordx2 v[58:59], v[62:63], off
	global_store_dwordx2 v[58:59], v[54:55], off offset:128
	s_and_saveexec_b64 s[0:1], s[6:7]
	s_cbranch_execz .LBB0_1436
;     __device__ __forceinline__ void operator()(f32x4 (&acc)[2][2][4][2], const Unit& u, int wr, int wc, int fr, int fq) const {
;     ...
; #pragma unroll
;         for (int ai = 0; ai < 2; ++ai)
; #pragma unroll
;             for (int m = 0; m < 4; ++m) {
;                 const int row = row0 + ai * HALF + m * 16;
;                 const float ss = __hip_atomic_load(SS + row, __ATOMIC_RELAXED, __HIP_MEMORY_SCOPE_AGENT);
;                 const float rstd = 1.0f / sqrtf(ss * (1.f / 1024.f) + 1e-6f);
;                 float qs = 0.f;
;                 if constexpr (!FINAL) {
;                     const float am = __uint_as_float(__hip_atomic_load(AM + row, __ATOMIC_RELAXED, __HIP_MEMORY_SCOPE_AGENT));
;                     qs = am > 0.f ? 127.f / am : 0.f;
;                     if (u.pn == 0 && wc == 0 && fq == 0) SH[row] = am * rstd * (1.f / 127.f);
;                 }
; #pragma unroll
;                 for (int bj = 0; bj < 2; ++bj) {
;                     const size_t off = (size_t)row * 1024 + col0 + bj * HALF;
;                     const f32x4 y0 = acc[ai][bj][m][0] * rstd * gv[bj][0], y1 = acc[ai][bj][m][1] * rstd * gv[bj][1];
;                     if constexpr (FINAL) { *(f32x4*)(out + off) = y0; *(f32x4*)(out + off + 4) = y1; }
;                     else {
;                         u32x2 q8; q8.x = q8x4(acc[ai][bj][m][0] * gv[bj][0], qs); q8.y = q8x4(acc[ai][bj][m][1] * gv[bj][1], qs);
;                         *(u32x2*)(H8 + off) = q8;
;                     }
;                 }
	s_waitcnt vmcnt(38)
	v_fmamk_f32 v51, v170, 0x3a800000, v240
	v_mul_f32_e32 v52, 0x4f800000, v51
	v_cmp_gt_f32_e32 vcc, s68, v51
	s_nop 1
	v_cndmask_b32_e32 v51, v51, v52, vcc
	v_sqrt_f32_e32 v52, v51
	s_nop 0
	v_add_u32_e32 v53, -1, v52
	v_fma_f32 v55, -v53, v52, v51
	v_add_u32_e32 v54, 1, v52
	v_cmp_ge_f32_e64 s[8:9], 0, v55
	s_nop 1
	v_cndmask_b32_e64 v53, v52, v53, s[8:9]
	v_fma_f32 v52, -v54, v52, v51
	v_cmp_lt_f32_e64 s[8:9], 0, v52
	s_nop 1
	v_cndmask_b32_e64 v52, v53, v54, s[8:9]
	v_mul_f32_e32 v53, 0x37800000, v52
	v_cndmask_b32_e32 v52, v52, v53, vcc
	v_cmp_class_f32_e32 vcc, v51, v241
	s_nop 1
	v_cndmask_b32_e32 v51, v52, v51, vcc
	v_div_scale_f32 v52, s[2:3], v51, v51, 1.0
	v_rcp_f32_e32 v53, v52
	s_nop 0
	v_fma_f32 v54, -v52, v53, 1.0
	v_fmac_f32_e32 v53, v54, v53
	v_div_scale_f32 v54, vcc, 1.0, v51, 1.0
	v_mul_f32_e32 v55, v54, v53
	v_fma_f32 v56, -v52, v55, v54
	v_fmac_f32_e32 v55, v56, v53
	v_fma_f32 v52, -v52, v55, v54
	v_div_fmas_f32 v52, v52, v53, v55
	v_div_fixup_f32 v51, v52, v51, 1.0
	v_mul_f32_e32 v51, v51, v171
	v_mul_f32_e32 v51, 0x3c010204, v51
	v_lshl_add_u64 v[52:53], v[222:223], 2, s[26:27]
	global_store_dword v[52:53], v51, off
.LBB0_1436:
	s_or_b64 exec, exec, s[0:1]
	s_waitcnt vmcnt(38)
	s_mov_b32 s98, 0xa0000
	s_mov_b32 s99, 0
	v_lshl_add_u64 v[148:149], v[146:147], 0, s[98:99]
	global_store_dwordx4 v[148:149], v[46:49], off
	global_store_dwordx4 v[148:149], v[42:45], off offset:16
	global_store_dwordx4 v[148:149], v[38:41], off offset:512
	global_store_dwordx4 v[148:149], v[34:37], off offset:528
	v_div_scale_f32 v51, s[0:1], v171, v171, s69
	v_rcp_f32_e32 v52, v51
	v_div_scale_f32 v53, vcc, s69, v171, s69
	v_pk_mul_f32 v[48:49], v[48:49], v[16:17]
	v_fma_f32 v54, -v51, v52, 1.0
	v_fmac_f32_e32 v52, v54, v52
	v_mul_f32_e32 v54, v53, v52
	v_fma_f32 v55, -v51, v54, v53
	v_fmac_f32_e32 v54, v55, v52
	v_fma_f32 v51, -v51, v54, v53
	v_div_fmas_f32 v51, v51, v52, v54
	v_div_fixup_f32 v51, v51, v171, s69
	v_cmp_lt_f32_e32 vcc, 0, v171
	v_pk_mul_f32 v[46:47], v[46:47], v[14:15]
	v_pk_mul_f32 v[44:45], v[44:45], v[12:13]
	v_cndmask_b32_e32 v50, 0, v51, vcc
	v_pk_mul_f32 v[42:43], v[42:43], v[10:11]
	v_pk_fma_f32 v[46:47], v[46:47], v[50:51], s[34:35] op_sel_hi:[1,0,0]
	v_pk_fma_f32 v[48:49], v[48:49], v[50:51], s[34:35] op_sel_hi:[1,0,0]
	v_pk_fma_f32 v[42:43], v[42:43], v[50:51], s[34:35] op_sel_hi:[1,0,0]
	v_pk_fma_f32 v[44:45], v[44:45], v[50:51], s[34:35] op_sel_hi:[1,0,0]
	v_pk_mul_f32 v[40:41], v[40:41], v[8:9]
	v_pk_mul_f32 v[38:39], v[38:39], v[6:7]
	v_pk_mul_f32 v[36:37], v[36:37], v[4:5]
	v_pk_mul_f32 v[34:35], v[34:35], v[2:3]
	v_lshlrev_b32_e32 v47, 8, v47
	v_lshlrev_b32_e32 v48, 16, v48
	v_lshlrev_b32_e32 v43, 8, v43
	v_lshlrev_b32_e32 v44, 16, v44
	v_pk_fma_f32 v[38:39], v[38:39], v[50:51], s[34:35] op_sel_hi:[1,0,0]
	v_pk_fma_f32 v[40:41], v[40:41], v[50:51], s[34:35] op_sel_hi:[1,0,0]
	v_pk_fma_f32 v[34:35], v[34:35], v[50:51], s[34:35] op_sel_hi:[1,0,0]
	v_pk_fma_f32 v[36:37], v[36:37], v[50:51], s[34:35] op_sel_hi:[1,0,0]
	v_lshlrev_b64 v[52:53], 10, v[222:223]
	v_and_b32_e32 v47, 0xff00, v47
	v_and_b32_e32 v48, 0xff0000, v48
	v_perm_b32 v46, v49, v46, s70
	v_and_b32_e32 v43, 0xff00, v43
	v_and_b32_e32 v44, 0xff0000, v44
	v_perm_b32 v42, v45, v42, s70
	v_lshlrev_b32_e32 v39, 8, v39
	v_lshlrev_b32_e32 v40, 16, v40
	v_lshlrev_b32_e32 v35, 8, v35
	v_lshlrev_b32_e32 v36, 16, v36
	v_or3_b32 v46, v46, v47, v48
	v_or3_b32 v47, v42, v43, v44
	v_lshl_add_u64 v[42:43], s[18:19], 0, v[52:53]
	v_and_b32_e32 v39, 0xff00, v39
	v_and_b32_e32 v40, 0xff0000, v40
	v_perm_b32 v38, v41, v38, s70
	v_and_b32_e32 v35, 0xff00, v35
	v_and_b32_e32 v36, 0xff0000, v36
	v_perm_b32 v34, v37, v34, s70
	v_lshl_add_u64 v[42:43], v[42:43], 0, v[210:211]
	v_or3_b32 v38, v38, v39, v40
	v_or3_b32 v39, v34, v35, v36
	global_store_dwordx2 v[42:43], v[46:47], off
	global_store_dwordx2 v[42:43], v[38:39], off offset:128
	s_and_saveexec_b64 s[0:1], s[6:7]
	s_cbranch_execz .LBB0_1438
	s_waitcnt vmcnt(42)
	v_fmamk_f32 v35, v172, 0x3a800000, v240
	v_mul_f32_e32 v36, 0x4f800000, v35
	v_cmp_gt_f32_e32 vcc, s68, v35
	s_nop 1
	v_cndmask_b32_e32 v35, v35, v36, vcc
	v_sqrt_f32_e32 v36, v35
	s_nop 0
	v_add_u32_e32 v37, -1, v36
	v_fma_f32 v39, -v37, v36, v35
	v_add_u32_e32 v38, 1, v36
	v_cmp_ge_f32_e64 s[6:7], 0, v39
	s_nop 1
	v_cndmask_b32_e64 v37, v36, v37, s[6:7]
	v_fma_f32 v36, -v38, v36, v35
	v_cmp_lt_f32_e64 s[6:7], 0, v36
	s_nop 1
	v_cndmask_b32_e64 v36, v37, v38, s[6:7]
	v_mul_f32_e32 v37, 0x37800000, v36
	v_cndmask_b32_e32 v36, v36, v37, vcc
	v_cmp_class_f32_e32 vcc, v35, v241
	s_nop 1
	v_cndmask_b32_e32 v35, v36, v35, vcc
	v_div_scale_f32 v36, s[2:3], v35, v35, 1.0
	v_rcp_f32_e32 v37, v36
	s_nop 0
	v_fma_f32 v38, -v36, v37, 1.0
	v_fmac_f32_e32 v37, v38, v37
	v_div_scale_f32 v38, vcc, 1.0, v35, 1.0
	v_mul_f32_e32 v39, v38, v37
	v_fma_f32 v40, -v36, v39, v38
	v_fmac_f32_e32 v39, v40, v37
	v_fma_f32 v36, -v36, v39, v38
	v_div_fmas_f32 v36, v36, v37, v39
	v_div_fixup_f32 v35, v36, v35, 1.0
	v_mul_f32_e32 v35, v35, v173
	v_mul_f32_e32 v35, 0x3c010204, v35
	v_lshl_add_u64 v[36:37], v[226:227], 2, s[26:27]
	global_store_dword v[36:37], v35, off
; #define PG8_BAR __builtin_amdgcn_s_barrier()
;     __device__ __forceinline__ void operator()(f32x4 (&acc)[2][2][4][2], const Unit& u, int wr, int wc, int fr, int fq) const {
;     ...
; #pragma unroll
;         for (int ai = 0; ai < 2; ++ai)
; #pragma unroll
;             for (int m = 0; m < 4; ++m) {
;                 const int row = row0 + ai * HALF + m * 16;
;                 const float ss = __hip_atomic_load(SS + row, __ATOMIC_RELAXED, __HIP_MEMORY_SCOPE_AGENT);
;                 const float rstd = 1.0f / sqrtf(ss * (1.f / 1024.f) + 1e-6f);
;                 float qs = 0.f;
;                 if constexpr (!FINAL) {
;                     const float am = __uint_as_float(__hip_atomic_load(AM + row, __ATOMIC_RELAXED, __HIP_MEMORY_SCOPE_AGENT));
;                     qs = am > 0.f ? 127.f / am : 0.f;
;                     if (u.pn == 0 && wc == 0 && fq == 0) SH[row] = am * rstd * (1.f / 127.f);
;                 }
; #pragma unroll
;                 for (int bj = 0; bj < 2; ++bj) {
;                     const size_t off = (size_t)row * 1024 + col0 + bj * HALF;
;                     const f32x4 y0 = acc[ai][bj][m][0] * rstd * gv[bj][0], y1 = acc[ai][bj][m][1] * rstd * gv[bj][1];
;                     if constexpr (FINAL) { *(f32x4*)(out + off) = y0; *(f32x4*)(out + off + 4) = y1; }
;                     else {
;                         u32x2 q8; q8.x = q8x4(acc[ai][bj][m][0] * gv[bj][0], qs); q8.y = q8x4(acc[ai][bj][m][1] * gv[bj][1], qs);
;                         *(u32x2*)(H8 + off) = q8;
;                     }
;                 }
; template <class Epi, class Sched, class Gemm, bool ALIGN_EPI = false, bool SP2 = false>
; __device__ __forceinline__ void gemm_phase(PG8_LAS unsigned char* lds, const Gemm g, const Sched& S, const Epi& E) {
;     ...
;         if (!has_next) break;
;         if constexpr (!epi_chain<Epi>::value) {
; #pragma unroll
;         for (int a = 0; a < 2; ++a)
; #pragma unroll
;             for (int b = 0; b < 2; ++b)
; #pragma unroll
;                 for (int m = 0; m < 4; ++m)
; #pragma unroll
;                     for (int n = 0; n < 2; ++n) acc[a][b][m][n] = (f32x4){0.f, 0.f, 0.f, 0.f};
;         }
;         cur = nxt; cA = nA; cB = nB; ++ui;
;         if constexpr (ALIGN_EPI) { if (wr == 1) PG8_BAR; }
.LBB0_1438:
	s_or_b64 exec, exec, s[0:1]
	s_waitcnt vmcnt(42)
	s_mov_b32 s98, 0xb0000
	s_mov_b32 s99, 0
	v_lshl_add_u64 v[148:149], v[146:147], 0, s[98:99]
	global_store_dwordx4 v[148:149], v[30:33], off
	global_store_dwordx4 v[148:149], v[26:29], off offset:16
	global_store_dwordx4 v[148:149], v[22:25], off offset:512
	global_store_dwordx4 v[148:149], v[18:21], off offset:528
	v_div_scale_f32 v35, s[0:1], v173, v173, s69
	v_rcp_f32_e32 v36, v35
	v_div_scale_f32 v37, vcc, s69, v173, s69
	v_pk_mul_f32 v[16:17], v[32:33], v[16:17]
	v_fma_f32 v38, -v35, v36, 1.0
	v_fmac_f32_e32 v36, v38, v36
	v_mul_f32_e32 v38, v37, v36
	v_fma_f32 v39, -v35, v38, v37
	v_fmac_f32_e32 v38, v39, v36
	v_fma_f32 v35, -v35, v38, v37
	v_div_fmas_f32 v35, v35, v36, v38
	v_div_fixup_f32 v35, v35, v173, s69
	v_cmp_lt_f32_e32 vcc, 0, v173
	v_pk_mul_f32 v[14:15], v[30:31], v[14:15]
	v_pk_mul_f32 v[12:13], v[28:29], v[12:13]
	v_cndmask_b32_e32 v34, 0, v35, vcc
	v_pk_mul_f32 v[10:11], v[26:27], v[10:11]
	v_pk_fma_f32 v[14:15], v[14:15], v[34:35], s[34:35] op_sel_hi:[1,0,0]
	v_pk_fma_f32 v[16:17], v[16:17], v[34:35], s[34:35] op_sel_hi:[1,0,0]
	v_pk_fma_f32 v[10:11], v[10:11], v[34:35], s[34:35] op_sel_hi:[1,0,0]
	v_pk_fma_f32 v[12:13], v[12:13], v[34:35], s[34:35] op_sel_hi:[1,0,0]
	v_pk_mul_f32 v[8:9], v[24:25], v[8:9]
	v_pk_mul_f32 v[6:7], v[22:23], v[6:7]
	v_pk_mul_f32 v[4:5], v[20:21], v[4:5]
	v_pk_mul_f32 v[2:3], v[18:19], v[2:3]
	v_lshlrev_b32_e32 v15, 8, v15
	v_lshlrev_b32_e32 v16, 16, v16
	v_lshlrev_b32_e32 v11, 8, v11
	v_lshlrev_b32_e32 v12, 16, v12
	v_pk_fma_f32 v[6:7], v[6:7], v[34:35], s[34:35] op_sel_hi:[1,0,0]
	v_pk_fma_f32 v[8:9], v[8:9], v[34:35], s[34:35] op_sel_hi:[1,0,0]
	v_pk_fma_f32 v[2:3], v[2:3], v[34:35], s[34:35] op_sel_hi:[1,0,0]
	v_pk_fma_f32 v[4:5], v[4:5], v[34:35], s[34:35] op_sel_hi:[1,0,0]
	v_lshlrev_b64 v[36:37], 10, v[226:227]
	v_and_b32_e32 v15, 0xff00, v15
	v_and_b32_e32 v16, 0xff0000, v16
	v_perm_b32 v14, v17, v14, s70
	v_and_b32_e32 v11, 0xff00, v11
	v_and_b32_e32 v12, 0xff0000, v12
	v_perm_b32 v10, v13, v10, s70
	v_lshlrev_b32_e32 v7, 8, v7
	v_lshlrev_b32_e32 v8, 16, v8
	v_lshlrev_b32_e32 v3, 8, v3
	v_lshlrev_b32_e32 v4, 16, v4
	v_or3_b32 v14, v14, v15, v16
	v_or3_b32 v15, v10, v11, v12
	v_lshl_add_u64 v[10:11], s[18:19], 0, v[36:37]
	v_and_b32_e32 v7, 0xff00, v7
	v_and_b32_e32 v8, 0xff0000, v8
	v_perm_b32 v6, v9, v6, s70
	v_and_b32_e32 v3, 0xff00, v3
	v_and_b32_e32 v4, 0xff0000, v4
	v_perm_b32 v2, v5, v2, s70
	v_lshl_add_u64 v[10:11], v[10:11], 0, v[210:211]
	v_or3_b32 v6, v6, v7, v8
	v_or3_b32 v7, v2, v3, v4
	s_andn2_b64 vcc, exec, s[4:5]
	s_mov_b64 s[0:1], -1
	global_store_dwordx2 v[10:11], v[14:15], off
	global_store_dwordx2 v[10:11], v[6:7], off offset:128
	s_cbranch_vccnz .LBB0_1362
	s_andn2_b64 vcc, exec, s[20:21]
	s_cbranch_vccnz .LBB0_1361
	s_barrier
	s_branch .LBB0_1361
